# v020 + G3 tile order: all 32 sample-panel tiles run in round 2 (slots of panels 8b+6/8b+7, columns 8..11), the displaced tiles in round 3, so the sample attention items no longer wait for round 3
# speedup vs baseline: 1.0121x; 1.0121x over previous
;     __device__ bool next(int i, Unit& u) const { const int L = i * G + c; if (L < 1536) return P.next(i, u); if (L < 1584) { u.pm = 32; u.pn = L - 1536; return true; } return false; }
;     __device__ bool next(int i, Unit& u) const { const int L = i * G + c; if (L < 256) return P.next(i, u); if (L < 264) { u.pm = 32; u.pn = L - 256; return true; } return false; }
;     __device__ bool next(int i, Unit& u) const {
;         if (G == 256) {
;             if (i < 4) {
;                 if (c < 8 && i >= 2) return false;
;                 P.next(i, u);
;                 if ((u.pm & 7) == 7 && (u.pn < 4 || (u.pn >= 8 && u.pn < 16))) {
;                     if (u.pn >= 8) { const int r = (u.pm >> 3) * 8 + (u.pn - 8); u.pm = 32; u.pn = r; }
;                     else { const int j = (u.pm >> 3) * 4 + u.pn; StaticOrder Q = P; Q.c = j & 7; Q.next(2 + (j >> 3), u); }
;                 }
;                 return true;
;             }
;             if (i == 4 && c >= 8 && c < 56) { const int r = c - 8; if (r < 32) { u.pm = 8 * (r >> 3) + 7; u.pn = 8 + (r & 7); } else { const int j = r - 32; u.pm = 8 * (j >> 2) + 7; u.pn = j & 3; } return true; }
.LBB0_407:
	s_andn2_b64 vcc, exec, s[2:3]
	s_cbranch_vccnz .LBB0_409
	s_cmp_gt_i32 s8, 11
	s_cbranch_scc1 .Lg3_swap
	s_and_b32 s2, s9, -8
	s_add_i32 s2, s8, s2
	s_add_i32 s6, s2, -8
	s_mov_b32 s10, 32
	s_branch .LBB0_409
.Lg3_swap:
	s_add_i32 s10, s9, -1
	s_add_i32 s6, s8, -4
.LBB0_409:
	s_mov_b32 s9, s10
	s_mov_b32 s8, s6
	s_branch .LBB0_410
.Lg3_m6:
	s_cmp_lg_u32 s2, 6
	s_cbranch_scc1 .LBB0_410
	s_and_b32 s6, s8, 0x7ffffffc
	s_cmp_lg_u32 s6, 8
	s_cbranch_scc1 .LBB0_410
	s_and_b32 s2, s9, -8
	s_add_i32 s2, s2, s8
	s_add_i32 s8, s2, -4
	s_mov_b32 s9, 32
